# P10 attention: prompt unit's staging issues the K/V loads of all three units of the workgroup; sample units only convert and write LDS
# speedup vs baseline: 1.0091x; 1.0091x over previous
.LBB0_1113:
	s_cmpk_gt_i32 s60, 0xff
	s_mov_b64 s[34:35], -1
	s_cbranch_scc0 .LBB0_1157
	s_add_i32 s34, s60, 0xffffff00
	s_and_b32 s35, s60, 3
	v_readfirstlane_b32 s36, v143
	s_and_b32 s67, s34, -4
	s_lshl_b32 s34, s34, 5
	s_lshr_b32 s61, s36, 6
	s_lshl_b32 s36, s35, 3
	v_add_u32_e32 v2, s67, v21
	v_mov_b32_e32 v3, v19
	s_and_b32 s76, s34, 0x7fffff80
	s_add_i32 s61, s61, s36
	v_lshlrev_b64 v[38:39], 12, v[2:3]
	v_or_b32_e32 v10, s76, v29
	v_mov_b32_e32 v11, v19
	v_readlane_b32 s80, v242, 31
	v_lshl_add_u64 v[2:3], s[50:51], 0, v[38:39]
	s_lshl_b32 s62, s61, 7
	v_lshlrev_b64 v[10:11], 10, v[10:11]
	v_readlane_b32 s86, v242, 37
	v_readlane_b32 s87, v242, 38
	v_lshl_add_u64 v[2:3], v[2:3], 0, s[62:63]
	s_lshl_b32 s62, s35, 8
	v_lshl_add_u64 v[10:11], s[86:87], 0, v[10:11]
	v_lshl_add_u64 v[10:11], v[10:11], 0, s[62:63]
	v_mov_b32_e32 v37, v19
	v_lshl_add_u64 v[2:3], v[2:3], 0, v[18:19]
	v_lshl_add_u64 v[14:15], v[10:11], 0, v[36:37]
	global_load_dwordx4 v[6:9], v[2:3], off
	s_nop 0
	global_load_dwordx4 v[2:5], v[2:3], off offset:64
	s_barrier
	v_lshrrev_b32_e32 v88, 3, v143
	v_and_b32_e32 v89, 7, v143
	v_and_b32_e32 v90, 0xff, v143
	v_lshrrev_b32_e32 v91, 8, v143
	v_mul_u32_u24_e32 v92, 0x90, v88
	v_lshl_add_u32 v92, v89, 4, v92
	v_mul_u32_u24_e32 v93, 0x1080, v91
	v_lshl_add_u32 v93, v90, 1, v93
	v_add_u32_e32 v94, 0x4200, v93
	v_add_u32_e32 v95, 0xffffff80, v90
	s_waitcnt vmcnt(0)
	s_cmpk_lt_i32 s60, 0x200
	s_cbranch_scc0 .Lat_setb
	v_cvt_pk_bf16_f32 v160, v160, v161
	v_cvt_pk_bf16_f32 v161, v162, v163
	v_cvt_pk_bf16_f32 v162, v164, v165
	v_cvt_pk_bf16_f32 v163, v166, v167
	v_cvt_pk_bf16_f32 v168, v168, v169
	v_cvt_pk_bf16_f32 v169, v170, v171
	v_cvt_pk_bf16_f32 v170, v172, v173
	v_cvt_pk_bf16_f32 v171, v174, v175
	ds_write_b128 v92, v[160:163]
	ds_write_b128 v92, v[168:171] offset:9216
	v_cmp_gt_u32_e32 vcc, 0x100, v143
	s_and_saveexec_b64 s[36:37], vcc
	ds_write_b128 v92, v[176:179] offset:18432
	s_mov_b64 exec, s[36:37]
	v_cmp_gt_u32_e32 vcc, 0x80, v90
	s_and_saveexec_b64 s[36:37], vcc
	v_cvt_pk_bf16_f32 v180, v180, v181
	v_cvt_pk_bf16_f32 v181, v182, v183
	v_cvt_pk_bf16_f32 v182, v184, v185
	v_cvt_pk_bf16_f32 v183, v186, v187
	v_cvt_pk_bf16_f32 v188, v188, v189
	v_cvt_pk_bf16_f32 v189, v190, v191
	v_cvt_pk_bf16_f32 v190, v192, v193
	v_cvt_pk_bf16_f32 v191, v194, v195
	v_cvt_pk_bf16_f32 v196, v196, v197
	v_cvt_pk_bf16_f32 v197, v198, v199
	v_cvt_pk_bf16_f32 v198, v200, v201
	v_cvt_pk_bf16_f32 v199, v202, v203
	v_cvt_pk_bf16_f32 v204, v204, v205
	v_cvt_pk_bf16_f32 v205, v206, v207
	v_cvt_pk_bf16_f32 v206, v208, v209
	v_cvt_pk_bf16_f32 v207, v210, v211
	s_mov_b64 exec, s[36:37]
	v_cmp_gt_u32_e32 vcc, 0xa0, v90
	s_and_saveexec_b64 s[36:37], vcc
	ds_write_b16 v93, v180 offset:36864
	ds_write_b16_d16_hi v93, v180 offset:37392
	ds_write_b16 v93, v181 offset:37920
	ds_write_b16_d16_hi v93, v181 offset:38448
	ds_write_b16 v93, v182 offset:38976
	ds_write_b16_d16_hi v93, v182 offset:39504
	ds_write_b16 v93, v183 offset:40032
	ds_write_b16_d16_hi v93, v183 offset:40560
	ds_write_b16 v93, v188 offset:45312
	ds_write_b16_d16_hi v93, v188 offset:45840
	ds_write_b16 v93, v189 offset:46368
	ds_write_b16_d16_hi v93, v189 offset:46896
	ds_write_b16 v93, v190 offset:47424
	ds_write_b16_d16_hi v93, v190 offset:47952
	ds_write_b16 v93, v191 offset:48480
	ds_write_b16_d16_hi v93, v191 offset:49008
	ds_write_b16 v94, v196 offset:36864
	ds_write_b16_d16_hi v94, v196 offset:37392
	ds_write_b16 v94, v197 offset:37920
	ds_write_b16_d16_hi v94, v197 offset:38448
	ds_write_b16 v94, v198 offset:38976
	ds_write_b16_d16_hi v94, v198 offset:39504
	ds_write_b16 v94, v199 offset:40032
	ds_write_b16_d16_hi v94, v199 offset:40560
	ds_write_b16 v94, v204 offset:45312
	ds_write_b16_d16_hi v94, v204 offset:45840
	ds_write_b16 v94, v205 offset:46368
	ds_write_b16_d16_hi v94, v205 offset:46896
	ds_write_b16 v94, v206 offset:47424
	ds_write_b16_d16_hi v94, v206 offset:47952
	ds_write_b16 v94, v207 offset:48480
	ds_write_b16_d16_hi v94, v207 offset:49008
	s_mov_b64 exec, s[36:37]
	s_branch .Lat_sdone
.Lat_setb:
	v_cvt_pk_bf16_f32 v116, v116, v117
	v_cvt_pk_bf16_f32 v117, v118, v119
	v_cvt_pk_bf16_f32 v118, v120, v121
	v_cvt_pk_bf16_f32 v119, v122, v123
	v_cvt_pk_bf16_f32 v124, v124, v125
	v_cvt_pk_bf16_f32 v125, v126, v127
	v_cvt_pk_bf16_f32 v126, v128, v129
	v_cvt_pk_bf16_f32 v127, v130, v131
	ds_write_b128 v92, v[116:119]
	ds_write_b128 v92, v[124:127] offset:9216
	v_cmp_gt_u32_e32 vcc, 0x100, v143
	s_and_saveexec_b64 s[36:37], vcc
	ds_write_b128 v92, v[132:135] offset:18432
	s_mov_b64 exec, s[36:37]
	v_cmp_gt_u32_e32 vcc, 0x80, v90
	s_and_saveexec_b64 s[36:37], vcc
	v_cvt_pk_bf16_f32 v136, v136, v137
	v_cvt_pk_bf16_f32 v137, v138, v139
	v_cvt_pk_bf16_f32 v138, v212, v213
	v_cvt_pk_bf16_f32 v139, v214, v215
	v_cvt_pk_bf16_f32 v216, v216, v217
	v_cvt_pk_bf16_f32 v217, v218, v219
	v_cvt_pk_bf16_f32 v218, v220, v221
	v_cvt_pk_bf16_f32 v219, v222, v223
	v_cvt_pk_bf16_f32 v224, v224, v225
	v_cvt_pk_bf16_f32 v225, v226, v227
	v_cvt_pk_bf16_f32 v226, v228, v229
	v_cvt_pk_bf16_f32 v227, v230, v231
	v_cvt_pk_bf16_f32 v232, v232, v233
	v_cvt_pk_bf16_f32 v233, v234, v235
	v_cvt_pk_bf16_f32 v234, v236, v237
	v_cvt_pk_bf16_f32 v235, v238, v239
	s_mov_b64 exec, s[36:37]
	v_cmp_gt_u32_e32 vcc, 0xa0, v90
	s_and_saveexec_b64 s[36:37], vcc
	ds_write_b16 v93, v136 offset:36864
	ds_write_b16_d16_hi v93, v136 offset:37392
	ds_write_b16 v93, v137 offset:37920
	ds_write_b16_d16_hi v93, v137 offset:38448
	ds_write_b16 v93, v138 offset:38976
	ds_write_b16_d16_hi v93, v138 offset:39504
	ds_write_b16 v93, v139 offset:40032
	ds_write_b16_d16_hi v93, v139 offset:40560
	ds_write_b16 v93, v216 offset:45312
	ds_write_b16_d16_hi v93, v216 offset:45840
	ds_write_b16 v93, v217 offset:46368
	ds_write_b16_d16_hi v93, v217 offset:46896
	ds_write_b16 v93, v218 offset:47424
	ds_write_b16_d16_hi v93, v218 offset:47952
	ds_write_b16 v93, v219 offset:48480
	ds_write_b16_d16_hi v93, v219 offset:49008
	ds_write_b16 v94, v224 offset:36864
	ds_write_b16_d16_hi v94, v224 offset:37392
	ds_write_b16 v94, v225 offset:37920
	ds_write_b16_d16_hi v94, v225 offset:38448
	ds_write_b16 v94, v226 offset:38976
	ds_write_b16_d16_hi v94, v226 offset:39504
	ds_write_b16 v94, v227 offset:40032
	ds_write_b16_d16_hi v94, v227 offset:40560
	ds_write_b16 v94, v232 offset:45312
	ds_write_b16_d16_hi v94, v232 offset:45840
	ds_write_b16 v94, v233 offset:46368
	ds_write_b16_d16_hi v94, v233 offset:46896
	ds_write_b16 v94, v234 offset:47424
	ds_write_b16_d16_hi v94, v234 offset:47952
	ds_write_b16 v94, v235 offset:48480
	ds_write_b16_d16_hi v94, v235 offset:49008
	s_mov_b64 exec, s[36:37]
.Lat_sdone:
	s_mov_b64 s[34:35], exec

.LBB0_1157:
	s_and_b64 vcc, exec, s[34:35]
	s_cbranch_vccz .LBB0_1112
	s_bfe_u32 s34, s60, 0x20004
	v_readfirstlane_b32 s35, v143
	s_lshr_b32 s67, s35, 6
	s_lshl_b32 s35, s34, 3
	s_and_b32 s61, s60, 15
	s_add_i32 s67, s67, s35
	s_lshl_b32 s35, s60, 5
	s_and_b32 s35, s35, 0xfffff800
	s_lshl_b32 s36, s61, 7
	s_or_b32 s66, s36, s35
	v_or_b32_e32 v2, s66, v1
	v_ashrrev_i32_e32 v3, 31, v2
	v_lshlrev_b64 v[2:3], 12, v[2:3]
	v_lshl_add_u64 v[2:3], s[50:51], 0, v[2:3]
	s_lshl_b32 s62, s67, 7
	v_lshl_add_u64 v[2:3], v[2:3], 0, s[62:63]
	v_lshl_add_u64 v[2:3], v[2:3], 0, v[18:19]
	global_load_dwordx4 v[14:17], v[2:3], off
	global_load_dwordx4 v[10:13], v[2:3], off offset:64
	s_lshl_b32 s76, s34, 6
	s_cmp_lg_u32 s61, 0
	s_cselect_b64 s[78:79], -1, 0
	s_addk_i32 s66, 0xff80
	s_cmp_eq_u32 s61, 0
	v_lshlrev_b32_e32 v38, 1, v20
	s_waitcnt lgkmcnt(0)
	s_barrier
	v_lshrrev_b32_e32 v88, 3, v143
	v_and_b32_e32 v89, 7, v143
	v_and_b32_e32 v90, 0xff, v143
	v_lshrrev_b32_e32 v91, 8, v143
	v_mul_u32_u24_e32 v92, 0x90, v88
	v_lshl_add_u32 v92, v89, 4, v92
	v_mul_u32_u24_e32 v93, 0x1080, v91
	v_lshl_add_u32 v93, v90, 1, v93
	v_add_u32_e32 v94, 0x4200, v93
	v_add_u32_e32 v95, 0xffffff80, v90
	s_lshl_b32 s62, s76, 1
	v_add_u32_e32 v96, s66, v88
	v_lshlrev_b32_e32 v96, 9, v96
	v_lshl_add_u32 v101, v89, 4, s62
	v_add_u32_e32 v96, v96, v101
	v_add_u32_e32 v97, 0x8000, v96
	v_add_u32_e32 v98, 0x10000, v96
	v_add_u32_e32 v99, 0x18000, v96
	v_add_u32_e32 v100, s66, v90
	v_lshlrev_b32_e32 v100, 9, v100
	v_lshl_add_u32 v101, v91, 4, s62
	v_add_u32_e32 v100, v100, v101
	s_cmp_eq_u32 s61, 0
	s_cbranch_scc1 .Lat_pfirst
	global_load_dwordx4 v[56:59], v96, s[48:49]
	global_load_dwordx4 v[60:63], v97, s[48:49]
	global_load_dwordx4 v[64:67], v98, s[48:49]
	global_load_dwordx4 v[68:71], v99, s[48:49]
	global_load_dwordx4 v[72:75], v100, s[54:55]
	global_load_dwordx4 v[76:79], v100, s[54:55] offset:32
	global_load_dwordx4 v[80:83], v100, s[54:55] offset:64
	global_load_dwordx4 v[84:87], v100, s[54:55] offset:96
	s_branch .Lat_pissued
.Lat_pfirst:
	v_mov_b32_e32 v56, 0
	v_mov_b32_e32 v57, 0
	v_mov_b32_e32 v58, 0
	v_mov_b32_e32 v59, 0
	v_mov_b32_e32 v60, 0
	v_mov_b32_e32 v61, 0
	v_mov_b32_e32 v62, 0
	v_mov_b32_e32 v63, 0
	v_mov_b32_e32 v72, 0
	v_mov_b32_e32 v73, 0
	v_mov_b32_e32 v74, 0
	v_mov_b32_e32 v75, 0
	v_mov_b32_e32 v76, 0
	v_mov_b32_e32 v77, 0
	v_mov_b32_e32 v78, 0
	v_mov_b32_e32 v79, 0
	v_mov_b32_e32 v80, 0
	v_mov_b32_e32 v81, 0
	v_mov_b32_e32 v82, 0
	v_mov_b32_e32 v83, 0
	v_mov_b32_e32 v84, 0
	v_mov_b32_e32 v85, 0
	v_mov_b32_e32 v86, 0
	v_mov_b32_e32 v87, 0
	global_load_dwordx4 v[64:67], v98, s[48:49]
	global_load_dwordx4 v[68:71], v99, s[48:49]
	v_cmp_lt_u32_e32 vcc, 0x7f, v90
	s_and_saveexec_b64 s[36:37], vcc
	global_load_dwordx4 v[72:75], v100, s[54:55]
	global_load_dwordx4 v[76:79], v100, s[54:55] offset:32
	global_load_dwordx4 v[80:83], v100, s[54:55] offset:64
	global_load_dwordx4 v[84:87], v100, s[54:55] offset:96
	s_mov_b64 exec, s[36:37]
.Lat_pissued:
	v_readlane_b32 s82, v242, 37
	v_readlane_b32 s83, v242, 38
	v_readlane_b32 s84, v242, 39
	v_readlane_b32 s85, v242, 40
	s_mov_b32 s35, s60
	s_and_b32 s86, s35, 3
	s_lshl_b32 s62, s86, 8
	s_lshl_b32 s87, s86, 7
	s_and_b32 s36, s35, -4
	s_add_i32 s36, s36, 0x2000
	s_lshl_b32 s37, s35, 5
	s_and_b32 s37, s37, 0x7fffff80
	v_add_u32_e32 v96, s37, v88
	v_lshlrev_b32_e32 v96, 10, v96
	v_lshl_add_u32 v101, v89, 5, s62
	v_add_u32_e32 v96, v96, v101
	v_add_u32_e32 v97, 0x10000, v96
	v_add_u32_e32 v98, s37, v90
	v_lshlrev_b32_e32 v98, 10, v98
	v_lshl_add_u32 v101, v91, 5, s62
	v_add_u32_e32 v98, v98, v101
	v_add_u32_e32 v99, s36, v88
	v_lshlrev_b32_e32 v99, 9, v99
	v_lshl_add_u32 v101, v89, 4, s87
	v_add_u32_e32 v99, v99, v101
	v_add_u32_e32 v100, s36, v95
	v_lshlrev_b32_e32 v100, 9, v100
	v_lshl_add_u32 v101, v91, 4, s87
	v_add_u32_e32 v100, v100, v101
	v_mov_b32_e32 v176, 0
	v_mov_b32_e32 v177, 0
	v_mov_b32_e32 v178, 0
	v_mov_b32_e32 v179, 0
	v_mov_b32_e32 v180, 0
	v_mov_b32_e32 v181, 0
	v_mov_b32_e32 v182, 0
	v_mov_b32_e32 v183, 0
	v_mov_b32_e32 v188, 0
	v_mov_b32_e32 v189, 0
	v_mov_b32_e32 v190, 0
	v_mov_b32_e32 v191, 0
	v_mov_b32_e32 v196, 0
	v_mov_b32_e32 v197, 0
	v_mov_b32_e32 v198, 0
	v_mov_b32_e32 v199, 0
	v_mov_b32_e32 v204, 0
	v_mov_b32_e32 v205, 0
	v_mov_b32_e32 v206, 0
	v_mov_b32_e32 v207, 0
	global_load_dwordx4 v[160:163], v96, s[82:83]
	global_load_dwordx4 v[164:167], v96, s[82:83] offset:16
	global_load_dwordx4 v[168:171], v97, s[82:83]
	global_load_dwordx4 v[172:175], v97, s[82:83] offset:16
	v_cmp_gt_u32_e32 vcc, 0x80, v90
	s_and_saveexec_b64 s[90:91], vcc
	global_load_dwordx4 v[180:183], v98, s[84:85] offset:0
	global_load_dwordx4 v[184:187], v98, s[84:85] offset:16
	global_load_dwordx4 v[188:191], v98, s[84:85] offset:64
	global_load_dwordx4 v[192:195], v98, s[84:85] offset:80
	global_load_dwordx4 v[196:199], v98, s[84:85] offset:128
	global_load_dwordx4 v[200:203], v98, s[84:85] offset:144
	global_load_dwordx4 v[204:207], v98, s[84:85] offset:192
	global_load_dwordx4 v[208:211], v98, s[84:85] offset:208
	s_mov_b64 exec, s[90:91]
	v_cmp_gt_u32_e32 vcc, 32, v143
	s_and_saveexec_b64 s[90:91], vcc
	global_load_dwordx4 v[176:179], v99, s[48:49]
	s_mov_b64 exec, s[90:91]
	v_cmp_gt_u32_e32 vcc, 4, v95
	s_and_saveexec_b64 s[90:91], vcc
	global_load_dwordx4 v[180:183], v100, s[54:55] offset:0
	global_load_dwordx4 v[188:191], v100, s[54:55] offset:32
	global_load_dwordx4 v[196:199], v100, s[54:55] offset:64
	global_load_dwordx4 v[204:207], v100, s[54:55] offset:96
	s_mov_b64 exec, s[90:91]
	s_add_i32 s35, s60, 0x100
	s_and_b32 s86, s35, 3
	s_lshl_b32 s62, s86, 8
	s_lshl_b32 s87, s86, 7
	s_and_b32 s36, s35, -4
	s_add_i32 s36, s36, 0x2000
	s_lshl_b32 s37, s35, 5
	s_and_b32 s37, s37, 0x7fffff80
	v_add_u32_e32 v96, s37, v88
	v_lshlrev_b32_e32 v96, 10, v96
	v_lshl_add_u32 v101, v89, 5, s62
	v_add_u32_e32 v96, v96, v101
	v_add_u32_e32 v97, 0x10000, v96
	v_add_u32_e32 v98, s37, v90
	v_lshlrev_b32_e32 v98, 10, v98
	v_lshl_add_u32 v101, v91, 5, s62
	v_add_u32_e32 v98, v98, v101
	v_add_u32_e32 v99, s36, v88
	v_lshlrev_b32_e32 v99, 9, v99
	v_lshl_add_u32 v101, v89, 4, s87
	v_add_u32_e32 v99, v99, v101
	v_add_u32_e32 v100, s36, v95
	v_lshlrev_b32_e32 v100, 9, v100
	v_lshl_add_u32 v101, v91, 4, s87
	v_add_u32_e32 v100, v100, v101
	v_mov_b32_e32 v132, 0
	v_mov_b32_e32 v133, 0
	v_mov_b32_e32 v134, 0
	v_mov_b32_e32 v135, 0
	v_mov_b32_e32 v136, 0
	v_mov_b32_e32 v137, 0
	v_mov_b32_e32 v138, 0
	v_mov_b32_e32 v139, 0
	v_mov_b32_e32 v216, 0
	v_mov_b32_e32 v217, 0
	v_mov_b32_e32 v218, 0
	v_mov_b32_e32 v219, 0
	v_mov_b32_e32 v224, 0
	v_mov_b32_e32 v225, 0
	v_mov_b32_e32 v226, 0
	v_mov_b32_e32 v227, 0
	v_mov_b32_e32 v232, 0
	v_mov_b32_e32 v233, 0
	v_mov_b32_e32 v234, 0
	v_mov_b32_e32 v235, 0
	global_load_dwordx4 v[116:119], v96, s[82:83]
	global_load_dwordx4 v[120:123], v96, s[82:83] offset:16
	global_load_dwordx4 v[124:127], v97, s[82:83]
	global_load_dwordx4 v[128:131], v97, s[82:83] offset:16
	v_cmp_gt_u32_e32 vcc, 0x80, v90
	s_and_saveexec_b64 s[90:91], vcc
	global_load_dwordx4 v[136:139], v98, s[84:85] offset:0
	global_load_dwordx4 v[212:215], v98, s[84:85] offset:16
	global_load_dwordx4 v[216:219], v98, s[84:85] offset:64
	global_load_dwordx4 v[220:223], v98, s[84:85] offset:80
	global_load_dwordx4 v[224:227], v98, s[84:85] offset:128
	global_load_dwordx4 v[228:231], v98, s[84:85] offset:144
	global_load_dwordx4 v[232:235], v98, s[84:85] offset:192
	global_load_dwordx4 v[236:239], v98, s[84:85] offset:208
	s_mov_b64 exec, s[90:91]
	v_cmp_gt_u32_e32 vcc, 32, v143
	s_and_saveexec_b64 s[90:91], vcc
	global_load_dwordx4 v[132:135], v99, s[48:49]
	s_mov_b64 exec, s[90:91]
	v_cmp_gt_u32_e32 vcc, 4, v95
	s_and_saveexec_b64 s[90:91], vcc
	global_load_dwordx4 v[136:139], v100, s[54:55] offset:0
	global_load_dwordx4 v[216:219], v100, s[54:55] offset:32
	global_load_dwordx4 v[224:227], v100, s[54:55] offset:64
	global_load_dwordx4 v[232:235], v100, s[54:55] offset:96
	s_mov_b64 exec, s[90:91]
	s_waitcnt vmcnt(0)
	ds_write_b128 v92, v[56:59]
	ds_write_b128 v92, v[60:63] offset:9216
	ds_write_b128 v92, v[64:67] offset:18432
	ds_write_b128 v92, v[68:71] offset:27648
	ds_write_b16 v93, v72 offset:36864
	ds_write_b16_d16_hi v93, v72 offset:37392
	ds_write_b16 v93, v73 offset:37920
	ds_write_b16_d16_hi v93, v73 offset:38448
	ds_write_b16 v93, v74 offset:38976
	ds_write_b16_d16_hi v93, v74 offset:39504
	ds_write_b16 v93, v75 offset:40032
	ds_write_b16_d16_hi v93, v75 offset:40560
	ds_write_b16 v93, v76 offset:45312
	ds_write_b16_d16_hi v93, v76 offset:45840
	ds_write_b16 v93, v77 offset:46368
	ds_write_b16_d16_hi v93, v77 offset:46896
	ds_write_b16 v93, v78 offset:47424
	ds_write_b16_d16_hi v93, v78 offset:47952
	ds_write_b16 v93, v79 offset:48480
	ds_write_b16_d16_hi v93, v79 offset:49008
	ds_write_b16 v94, v80 offset:36864
	ds_write_b16_d16_hi v94, v80 offset:37392
	ds_write_b16 v94, v81 offset:37920
	ds_write_b16_d16_hi v94, v81 offset:38448
	ds_write_b16 v94, v82 offset:38976
	ds_write_b16_d16_hi v94, v82 offset:39504
	ds_write_b16 v94, v83 offset:40032
	ds_write_b16_d16_hi v94, v83 offset:40560
	ds_write_b16 v94, v84 offset:45312
	ds_write_b16_d16_hi v94, v84 offset:45840
	ds_write_b16 v94, v85 offset:46368
	ds_write_b16_d16_hi v94, v85 offset:46896
	ds_write_b16 v94, v86 offset:47424
	ds_write_b16_d16_hi v94, v86 offset:47952
	ds_write_b16 v94, v87 offset:48480
	ds_write_b16_d16_hi v94, v87 offset:49008
	s_mov_b32 s66, 0
	s_lshl_b32 s34, s67, 2
	v_readlane_b32 s80, v242, 0
	v_mov_b32_e32 v2, s34
	v_readlane_b32 s81, v242, 1
	s_waitcnt lgkmcnt(0)
	s_barrier
	v_and_b32_e32 v3, 64, v53
	v_add_u32_e32 v3, 64, v3
	s_nop 0
	global_load_dword v37, v2, s[80:81]
	v_xor_b32_e32 v2, 16, v53
	v_cmp_lt_i32_e32 vcc, v2, v3
	s_and_b32 s36, s59, 15
	s_lshl_b32 s34, s67, 6
	v_cndmask_b32_e32 v2, v53, v2, vcc
	v_lshlrev_b32_e32 v55, 2, v2
	v_xor_b32_e32 v2, 32, v53
	v_cmp_lt_i32_e32 vcc, v2, v3
	s_and_b32 s35, s42, 0xfffff800
	s_lshl_b32 s36, s36, 7
	v_cndmask_b32_e32 v2, v53, v2, vcc
	s_or_b32 s35, s35, s36
	v_lshlrev_b32_e32 v56, 2, v2
	s_lshl_b32 s62, s34, 1
	v_mov_b64_e32 v[2:3], v[10:11]
	v_mov_b64_e32 v[6:7], v[14:15]
	v_lshl_add_u64 v[38:39], v[34:35], 0, s[62:63]
	v_or_b32_e32 v57, s35, v1
	s_mov_b32 s34, 0
	v_mov_b64_e32 v[4:5], v[12:13]
	v_mov_b64_e32 v[8:9], v[16:17]
	v_readlane_b32 s82, v242, 2
	v_readlane_b32 s83, v242, 3
	v_readlane_b32 s84, v242, 4
	v_readlane_b32 s85, v242, 5
	v_readlane_b32 s86, v242, 6
	v_readlane_b32 s87, v242, 7
	s_branch .LBB0_1177
